# sweep 1 far tiles: one running-max/sum update per 64-key tile and map instead of per 32-key half (about 40 fewer VALU per tile)
# speedup vs baseline: 1.0033x; 1.0008x over previous
; #define SBAR() __builtin_amdgcn_sched_barrier(0)
; __device__ __forceinline__ void stat_upd(const f32x16& p0, float& m, float& l, const float C, const float cb) {
;   float mx = p0[0];
; #pragma unroll
;   for (int r = 1; r < 16; ++r) mx = fmaxf(mx, p0[r]);
;   { auto rr = __builtin_amdgcn_permlane32_swap(__float_as_uint(mx), __float_as_uint(mx), false, false);
;     mx = fmaxf(__uint_as_float(rr[0]), __uint_as_float(rr[1])); }
;   mx += cb;
;   const float mn = fmaxf(m, mx), alpha = __builtin_amdgcn_exp2f((m - mn) * C), mnC = (cb - mn) * C; float s = 0.f;
; #pragma unroll
;   for (int r = 0; r < 16; ++r) s += __builtin_amdgcn_exp2f(fmaf(p0[r], C, mnC));
;   l = l * alpha + s; m = mn;
; }
; template <bool DIFF> ...
;     ...
;       qkt<DIFF>(a0, b0, K_lds, Q_lds, r32, r32, hi);
;       qkt<DIFF>(a1, b1, K_lds, Q_lds, r32 + 32, r32, hi);
;       SBAR();
;       float cb0, cb1;
;       BIAS_APPLY(t, 0, a0, b0, cb0);
;       stat_upd(a0, m1, l1, C, cb0);
;       if (DIFF) stat_upd(b0, m2, l2, C, cb0);
;       SBAR();
;       BIAS_APPLY(t, 1, a1, b1, cb1);
;       stat_upd(a1, m1, l1, C, cb1);
;       if (DIFF) stat_upd(b1, m2, l2, C, cb1);
.Lsw1f_hi:
	v_mov_b32_e32 v234, v253
	s_branch .Lsw1f
.Lsw1f_lo:
	v_mov_b32_e32 v234, v252
.Lsw1f:
	ds_read_b128 v[0:3], v176
	ds_read_b128 v[4:7], v172 offset:36864
	v_add_u32_e32 v177, v97, v93
	ds_read_b128 v[8:11], v177
	ds_read_b128 v[12:15], v176 offset:8192
	s_waitcnt lgkmcnt(2)
	v_mfma_f32_32x32x16_bf16 v[48:63], v[0:3], v[4:7], 0
	ds_read_b128 v[0:3], v171 offset:36864
	ds_read_b128 v[64:67], v177 offset:8192
	v_add_u32_e32 v178, v97, v90
	v_add_u32_e32 v179, v97, v94
	v_add_u32_e32 v180, v97, v91
	v_add_u32_e32 v181, v97, v95
	v_add_u32_e32 v182, v97, v92
	v_add_u32_e32 v183, v97, v96
	s_waitcnt lgkmcnt(1)
	v_mfma_f32_32x32x16_bf16 v[32:47], v[8:11], v[0:3], 0
	ds_read_b128 v[8:11], v178
	ds_read_b128 v[68:71], v170 offset:36864
	ds_read_b128 v[16:19], v179
	ds_read_b128 v[100:103], v178 offset:8192
	ds_read_b128 v[104:107], v169 offset:36864
	ds_read_b128 v[108:111], v179 offset:8192
	s_waitcnt lgkmcnt(1)
	v_mfma_f32_32x32x16_bf16 v[32:47], v[16:19], v[104:107], v[32:47]
	v_mfma_f32_32x32x16_bf16 v[48:63], v[8:11], v[68:71], v[48:63]
	ds_read_b128 v[8:11], v180
	ds_read_b128 v[112:115], v168 offset:36864
	ds_read_b128 v[16:19], v181
	ds_read_b128 v[116:119], v180 offset:8192
	ds_read_b128 v[120:123], v167 offset:36864
	ds_read_b128 v[124:127], v181 offset:8192
	s_waitcnt lgkmcnt(1)
	v_mfma_f32_32x32x16_bf16 v[32:47], v[16:19], v[120:123], v[32:47]
	v_mfma_f32_32x32x16_bf16 v[48:63], v[8:11], v[112:115], v[48:63]
	ds_read_b128 v[8:11], v182
	ds_read_b128 v[136:139], v166 offset:36864
	ds_read_b128 v[16:19], v183
	ds_read_b128 v[140:143], v182 offset:8192
	ds_read_b128 v[150:153], v149 offset:36864
	ds_read_b128 v[184:187], v183 offset:8192
	s_waitcnt lgkmcnt(1)
	v_mfma_f32_32x32x16_bf16 v[32:47], v[16:19], v[150:153], v[32:47]
	v_mfma_f32_32x32x16_bf16 v[16:31], v[12:15], v[4:7], 0
	v_mfma_f32_32x32x16_bf16 v[16:31], v[100:103], v[68:71], v[16:31]
	v_add_co_u32_e32 v68, vcc, s66, v84
	s_nop 1
	v_addc_co_u32_e32 v69, vcc, 0, v85, vcc
	global_load_dwordx4 v[68:71], v[68:69], off
	v_mfma_f32_32x32x16_bf16 v[48:63], v[8:11], v[136:139], v[48:63]
	v_mfma_f32_32x32x16_bf16 v[0:15], v[64:67], v[0:3], 0
	global_load_dwordx4 v[64:67], v[84:85], off
	v_mfma_f32_32x32x16_bf16 v[0:15], v[108:111], v[104:107], v[0:15]
	v_mfma_f32_32x32x16_bf16 v[16:31], v[116:119], v[112:115], v[16:31]
	v_mfma_f32_32x32x16_bf16 v[0:15], v[124:127], v[120:123], v[0:15]
	v_mfma_f32_32x32x16_bf16 v[16:31], v[140:143], v[136:139], v[16:31]
	s_waitcnt lgkmcnt(0)
	v_mfma_f32_32x32x16_bf16 v[0:15], v[184:187], v[150:153], v[0:15]
	v_max3_f32 v236, v48, v49, v50
	v_max3_f32 v236, v236, v51, v52
	v_max3_f32 v236, v236, v53, v54
	v_max3_f32 v236, v236, v55, v56
	v_max3_f32 v236, v236, v57, v58
	v_max3_f32 v236, v236, v59, v60
	v_max3_f32 v236, v236, v61, v62
	v_max_f32_e32 v236, v236, v63
	v_max3_f32 v241, v32, v33, v34
	v_max3_f32 v241, v241, v35, v36
	v_max3_f32 v241, v241, v37, v38
	v_max3_f32 v241, v241, v39, v40
	v_max3_f32 v241, v241, v41, v42
	v_max3_f32 v241, v241, v43, v44
	v_max3_f32 v241, v241, v45, v46
	v_max_f32_e32 v241, v241, v47
	v_max3_f32 v236, v236, v16, v17
	v_max3_f32 v236, v236, v18, v19
	v_max3_f32 v236, v236, v20, v21
	v_max3_f32 v236, v236, v22, v23
	v_max3_f32 v236, v236, v24, v25
	v_max3_f32 v236, v236, v26, v27
	v_max3_f32 v236, v236, v28, v29
	v_max3_f32 v236, v236, v30, v31
	v_max3_f32 v241, v241, v0, v1
	v_max3_f32 v241, v241, v2, v3
	v_max3_f32 v241, v241, v4, v5
	v_max3_f32 v241, v241, v6, v7
	v_max3_f32 v241, v241, v8, v9
	v_max3_f32 v241, v241, v10, v11
	v_max3_f32 v241, v241, v12, v13
	v_max3_f32 v241, v241, v14, v15
	v_mov_b32_e32 v237, v236
	v_mov_b32_e32 v242, v241
	s_nop 1
	v_permlane32_swap_b32_e32 v236, v237
	v_permlane32_swap_b32_e32 v241, v242
	v_max_f32_e32 v236, v236, v237
	v_add_f32_e32 v236, v234, v236
	v_max_f32_e32 v240, v87, v236
	v_sub_f32_e32 v238, v234, v240
	v_mul_f32_e32 v238, 0x3e38aa3b, v238
	v_sub_f32_e32 v239, v87, v240
	v_mul_f32_e32 v239, 0x3e38aa3b, v239
	v_exp_f32_e32 v239, v239
	v_mov_b32_e32 v87, v240
	v_max_f32_e32 v241, v241, v242
	v_add_f32_e32 v241, v234, v241
	v_max_f32_e32 v245, v81, v241
	v_sub_f32_e32 v243, v234, v245
	v_mul_f32_e32 v243, 0x3e38aa3b, v243
	v_sub_f32_e32 v244, v81, v245
	v_mul_f32_e32 v244, 0x3e38aa3b, v244
	v_exp_f32_e32 v244, v244
	v_mov_b32_e32 v81, v245
	v_fmamk_f32 v48, v48, 0x3e38aa3b, v238
	v_fmamk_f32 v49, v49, 0x3e38aa3b, v238
	v_fmamk_f32 v50, v50, 0x3e38aa3b, v238
	v_fmamk_f32 v51, v51, 0x3e38aa3b, v238
	v_fmamk_f32 v52, v52, 0x3e38aa3b, v238
	v_fmamk_f32 v53, v53, 0x3e38aa3b, v238
	v_fmamk_f32 v54, v54, 0x3e38aa3b, v238
	v_fmamk_f32 v55, v55, 0x3e38aa3b, v238
	v_fmamk_f32 v56, v56, 0x3e38aa3b, v238
	v_fmamk_f32 v57, v57, 0x3e38aa3b, v238
	v_fmamk_f32 v58, v58, 0x3e38aa3b, v238
	v_fmamk_f32 v59, v59, 0x3e38aa3b, v238
	v_fmamk_f32 v60, v60, 0x3e38aa3b, v238
	v_fmamk_f32 v61, v61, 0x3e38aa3b, v238
	v_fmamk_f32 v62, v62, 0x3e38aa3b, v238
	v_fmamk_f32 v63, v63, 0x3e38aa3b, v238
	v_fmamk_f32 v16, v16, 0x3e38aa3b, v238
	v_fmamk_f32 v17, v17, 0x3e38aa3b, v238
	v_fmamk_f32 v18, v18, 0x3e38aa3b, v238
	v_fmamk_f32 v19, v19, 0x3e38aa3b, v238
	v_fmamk_f32 v20, v20, 0x3e38aa3b, v238
	v_fmamk_f32 v21, v21, 0x3e38aa3b, v238
; #define SBAR() __builtin_amdgcn_sched_barrier(0)
; __device__ __forceinline__ void stat_upd(const f32x16& p0, float& m, float& l, const float C, const float cb) {
;     ...
;   const float mn = fmaxf(m, mx), alpha = __builtin_amdgcn_exp2f((m - mn) * C), mnC = (cb - mn) * C; float s = 0.f;
; #pragma unroll
;   for (int r = 0; r < 16; ++r) s += __builtin_amdgcn_exp2f(fmaf(p0[r], C, mnC));
;   l = l * alpha + s; m = mn;
; template <bool DIFF> ...
;     ...
;       stat_upd(a0, m1, l1, C, cb0);
;       if (DIFF) stat_upd(b0, m2, l2, C, cb0);
;       SBAR();
;       BIAS_APPLY(t, 1, a1, b1, cb1);
;       stat_upd(a1, m1, l1, C, cb1);
;       if (DIFF) stat_upd(b1, m2, l2, C, cb1);
	v_fmamk_f32 v22, v22, 0x3e38aa3b, v238
	v_fmamk_f32 v23, v23, 0x3e38aa3b, v238
	v_fmamk_f32 v24, v24, 0x3e38aa3b, v238
	v_fmamk_f32 v25, v25, 0x3e38aa3b, v238
	v_fmamk_f32 v26, v26, 0x3e38aa3b, v238
	v_fmamk_f32 v27, v27, 0x3e38aa3b, v238
	v_fmamk_f32 v28, v28, 0x3e38aa3b, v238
	v_fmamk_f32 v29, v29, 0x3e38aa3b, v238
	v_fmamk_f32 v30, v30, 0x3e38aa3b, v238
	v_fmamk_f32 v31, v31, 0x3e38aa3b, v238
	v_exp_f32_e32 v48, v48
	v_exp_f32_e32 v49, v49
	v_exp_f32_e32 v50, v50
	v_exp_f32_e32 v51, v51
	v_exp_f32_e32 v52, v52
	v_exp_f32_e32 v53, v53
	v_exp_f32_e32 v54, v54
	v_exp_f32_e32 v55, v55
	v_exp_f32_e32 v56, v56
	v_add_f32_e32 v48, v48, v52
	v_exp_f32_e32 v57, v57
	v_add_f32_e32 v49, v49, v53
	v_exp_f32_e32 v58, v58
	v_add_f32_e32 v50, v50, v54
	v_exp_f32_e32 v59, v59
	v_add_f32_e32 v51, v51, v55
	v_exp_f32_e32 v60, v60
	v_add_f32_e32 v48, v48, v56
	v_exp_f32_e32 v61, v61
	v_add_f32_e32 v49, v49, v57
	v_exp_f32_e32 v62, v62
	v_add_f32_e32 v50, v50, v58
	v_exp_f32_e32 v63, v63
	v_add_f32_e32 v51, v51, v59
	v_exp_f32_e32 v16, v16
	v_add_f32_e32 v48, v48, v60
	v_exp_f32_e32 v17, v17
	v_add_f32_e32 v49, v49, v61
	v_exp_f32_e32 v18, v18
	v_add_f32_e32 v50, v50, v62
	v_exp_f32_e32 v19, v19
	v_add_f32_e32 v51, v51, v63
	v_exp_f32_e32 v20, v20
	v_add_f32_e32 v48, v48, v16
	v_exp_f32_e32 v21, v21
	v_add_f32_e32 v49, v49, v17
	v_exp_f32_e32 v22, v22
	v_add_f32_e32 v50, v50, v18
	v_exp_f32_e32 v23, v23
	v_add_f32_e32 v51, v51, v19
	v_exp_f32_e32 v24, v24
	v_add_f32_e32 v48, v48, v20
	v_exp_f32_e32 v25, v25
	v_add_f32_e32 v49, v49, v21
	v_exp_f32_e32 v26, v26
	v_add_f32_e32 v50, v50, v22
	v_exp_f32_e32 v27, v27
	v_add_f32_e32 v51, v51, v23
	v_exp_f32_e32 v28, v28
	v_add_f32_e32 v48, v48, v24
	v_exp_f32_e32 v29, v29
	v_add_f32_e32 v49, v49, v25
	v_exp_f32_e32 v30, v30
	v_add_f32_e32 v50, v50, v26
	v_exp_f32_e32 v31, v31
	v_add_f32_e32 v51, v51, v27
	v_add_f32_e32 v48, v48, v28
	v_add_f32_e32 v49, v49, v29
	v_add_f32_e32 v50, v50, v30
	v_add_f32_e32 v51, v51, v31
	v_add_f32_e32 v48, v48, v49
	v_add_f32_e32 v50, v50, v51
	v_add_f32_e32 v48, v48, v50
	v_fma_f32 v83, v83, v239, v48
	v_fmamk_f32 v32, v32, 0x3e38aa3b, v243
	v_fmamk_f32 v33, v33, 0x3e38aa3b, v243
	v_fmamk_f32 v34, v34, 0x3e38aa3b, v243
	v_fmamk_f32 v35, v35, 0x3e38aa3b, v243
	v_fmamk_f32 v36, v36, 0x3e38aa3b, v243
	v_fmamk_f32 v37, v37, 0x3e38aa3b, v243
	v_fmamk_f32 v38, v38, 0x3e38aa3b, v243
	v_fmamk_f32 v39, v39, 0x3e38aa3b, v243
	v_fmamk_f32 v40, v40, 0x3e38aa3b, v243
	v_fmamk_f32 v41, v41, 0x3e38aa3b, v243
	v_fmamk_f32 v42, v42, 0x3e38aa3b, v243
	v_fmamk_f32 v43, v43, 0x3e38aa3b, v243
	v_fmamk_f32 v44, v44, 0x3e38aa3b, v243
	v_fmamk_f32 v45, v45, 0x3e38aa3b, v243
	v_fmamk_f32 v46, v46, 0x3e38aa3b, v243
	v_fmamk_f32 v47, v47, 0x3e38aa3b, v243
	v_fmamk_f32 v0, v0, 0x3e38aa3b, v243
	v_fmamk_f32 v1, v1, 0x3e38aa3b, v243
	v_fmamk_f32 v2, v2, 0x3e38aa3b, v243
	v_fmamk_f32 v3, v3, 0x3e38aa3b, v243
	v_fmamk_f32 v4, v4, 0x3e38aa3b, v243
	v_fmamk_f32 v5, v5, 0x3e38aa3b, v243
	v_fmamk_f32 v6, v6, 0x3e38aa3b, v243
	v_fmamk_f32 v7, v7, 0x3e38aa3b, v243
	v_fmamk_f32 v8, v8, 0x3e38aa3b, v243
	v_fmamk_f32 v9, v9, 0x3e38aa3b, v243
	v_fmamk_f32 v10, v10, 0x3e38aa3b, v243
	v_fmamk_f32 v11, v11, 0x3e38aa3b, v243
	v_fmamk_f32 v12, v12, 0x3e38aa3b, v243
	v_fmamk_f32 v13, v13, 0x3e38aa3b, v243
	v_fmamk_f32 v14, v14, 0x3e38aa3b, v243
	v_fmamk_f32 v15, v15, 0x3e38aa3b, v243
	v_exp_f32_e32 v32, v32
	v_exp_f32_e32 v33, v33
	v_exp_f32_e32 v34, v34
	v_exp_f32_e32 v35, v35
	v_exp_f32_e32 v36, v36
	v_exp_f32_e32 v37, v37
	v_exp_f32_e32 v38, v38
	v_exp_f32_e32 v39, v39
	v_exp_f32_e32 v40, v40
	v_add_f32_e32 v32, v32, v36
	v_exp_f32_e32 v41, v41
	v_add_f32_e32 v33, v33, v37
	v_exp_f32_e32 v42, v42
	v_add_f32_e32 v34, v34, v38
	v_exp_f32_e32 v43, v43
	v_add_f32_e32 v35, v35, v39
	v_exp_f32_e32 v44, v44
	v_add_f32_e32 v32, v32, v40
	v_exp_f32_e32 v45, v45
	v_add_f32_e32 v33, v33, v41
	v_exp_f32_e32 v46, v46
	v_add_f32_e32 v34, v34, v42
	v_exp_f32_e32 v47, v47
	v_add_f32_e32 v35, v35, v43
	v_exp_f32_e32 v0, v0
	v_add_f32_e32 v32, v32, v44
	v_exp_f32_e32 v1, v1
	v_add_f32_e32 v33, v33, v45
	v_exp_f32_e32 v2, v2
	v_add_f32_e32 v34, v34, v46
	v_exp_f32_e32 v3, v3
	v_add_f32_e32 v35, v35, v47
	v_exp_f32_e32 v4, v4
	v_add_f32_e32 v32, v32, v0
	v_exp_f32_e32 v5, v5
	v_add_f32_e32 v33, v33, v1
	v_exp_f32_e32 v6, v6
	v_add_f32_e32 v34, v34, v2
	v_exp_f32_e32 v7, v7
	v_add_f32_e32 v35, v35, v3
	v_exp_f32_e32 v8, v8
	v_add_f32_e32 v32, v32, v4
	v_exp_f32_e32 v9, v9
	v_add_f32_e32 v33, v33, v5
	v_exp_f32_e32 v10, v10
	v_add_f32_e32 v34, v34, v6
	v_exp_f32_e32 v11, v11
	v_add_f32_e32 v35, v35, v7
	v_exp_f32_e32 v12, v12
	v_add_f32_e32 v32, v32, v8
	v_exp_f32_e32 v13, v13
	v_add_f32_e32 v33, v33, v9
	v_exp_f32_e32 v14, v14
	v_add_f32_e32 v34, v34, v10
	v_exp_f32_e32 v15, v15
	v_add_f32_e32 v35, v35, v11
	v_add_f32_e32 v32, v32, v12
	v_add_f32_e32 v33, v33, v13
	v_add_f32_e32 v34, v34, v14
	v_add_f32_e32 v35, v35, v15
	v_add_f32_e32 v32, v32, v33
	v_add_f32_e32 v34, v34, v35
	v_add_f32_e32 v32, v32, v34
	v_fma_f32 v82, v82, v244, v32
	s_add_i32 s2, s2, 64
	s_cmp_eq_u32 s18, s2
	v_lshl_add_u64 v[84:85], v[84:85], 0, s[26:27]
	s_cbranch_scc1 .LBB0_292
	s_branch .LBB0_276
